# weight-copy queue: next-piece ticket atomic returns under the piece (no immediate wait)
# speedup vs baseline: 1.0092x; 1.0004x over previous
.LBB0_240:
	s_and_b32 s4, s43, 1
	s_and_saveexec_b64 s[0:1], s[40:41]
	s_lshl_b32 s5, s4, 2
	s_add_i32 s5, s5, 0
	s_add_i32 s5, s5, 0x20830
	v_mov_b32_e32 v0, s5
	ds_write_b32 v0, v66
	s_or_b64 exec, exec, s[0:1]
	s_lshl_b32 s0, s4, 2
	s_add_i32 s0, s0, 0
	s_add_i32 s0, s0, 0x20830
	v_mov_b32_e32 v0, s0
	s_waitcnt lgkmcnt(0)
	s_barrier
	ds_read_b32 v0, v0
	s_mov_b64 s[0:1], -1
	s_waitcnt lgkmcnt(0)
	v_readfirstlane_b32 s4, v0
	s_cmp_ge_i32 s4, s42
	v_readfirstlane_b32 s5, v0
	s_cbranch_scc1 .LBB0_239
	s_and_saveexec_b64 s[0:1], s[40:41]
	s_cbranch_execz .LBB0_247
	s_mov_b64 s[36:37], exec
	v_mbcnt_lo_u32_b32 v0, s36, 0
	v_mbcnt_hi_u32_b32 v0, s37, v0
	v_cmp_eq_u32_e32 vcc, 0, v0
	s_and_saveexec_b64 s[28:29], vcc
	s_cbranch_execz .LBB0_246
	s_bcnt1_i32_b64 s5, s[36:37]
	v_mov_b32_e32 v1, s5
	global_atomic_add v66, v65, v1, s[16:17] sc0
.LBB0_246:
	s_or_b64 exec, exec, s[28:29]
.LBB0_247:
	s_or_b64 exec, exec, s[0:1]
	s_lshl_b32 s50, s4, 4
	s_cmpk_gt_i32 s4, 0x11f
	v_readlane_b32 s0, v254, 49
	s_cselect_b64 s[62:63], -1, 0
	s_add_i32 s50, s50, s0
	s_mov_b32 s0, 0
	s_mov_b64 s[48:49], -1
	s_branch .LBB0_250
